# attention O-store epilogue: neighbour-lane exchange via DPP quad_perm instead of 64 serialized ds_bpermute round trips per item
# baseline (speedup 1.0000x reference)
.LBB0_527:
	s_waitcnt vmcnt(8)
	v_lshl_add_u32 v64, v171, 2, 0
	v_add_u32_e32 v64, 0x10800, v64
	s_waitcnt vmcnt(11)
	ds_write_b128 v174, v[120:123] offset:32768
	s_waitcnt vmcnt(8)
	ds_write_b128 v174, v[124:127] offset:40960
	ds_write_b32 v64, v136
	v_cmp_gt_u32_e32 vcc, 32, v171
	s_and_saveexec_b64 s[38:39], vcc
	ds_write_b32 v176, v96
	s_or_b64 exec, exec, s[38:39]
	s_waitcnt lgkmcnt(0)
	ds_read_b128 v[76:79], v175
	ds_read_b128 v[72:75], v175 offset:32
	v_and_b32_e32 v80, 64, v239
	v_add_u32_e32 v80, 64, v80
	ds_read_b128 v[68:71], v175 offset:64
	ds_read_b128 v[64:67], v175 offset:96
	s_waitcnt lgkmcnt(3)
	v_rcp_f32_e32 v82, v76
	v_xor_b32_e32 v76, 1, v239
	v_cmp_lt_i32_e32 vcc, v76, v80
	s_mul_hi_i32 s1, s30, 0x1080
	v_mul_f32_e32 v48, v48, v82
	v_cndmask_b32_e32 v76, v239, v76, vcc
	v_lshlrev_b32_e32 v76, 2, v76
	s_mulk_i32 s30, 0x1080
	s_nop 1
	v_mov_b32_dpp v83, v48 quad_perm:[1,0,3,2] row_mask:0xf bank_mask:0xf
	s_add_u32 s0, s52, s30
	s_addc_u32 s1, s53, s1
	v_and_b32_e32 v80, 1, v170
	v_lshlrev_b32_e32 v138, 1, v173
	v_cmp_eq_u32_e64 s[38:39], 0, v80
	v_lshl_add_u64 v[80:81], s[0:1], 0, v[138:139]
	v_mul_u32_u24_e32 v138, 0x4200, v172
	v_lshl_add_u64 v[80:81], v[80:81], 0, v[138:139]
	s_and_saveexec_b64 s[40:41], s[38:39]
	s_cbranch_execz .LBB0_531
	s_waitcnt lgkmcnt(0)
	v_cvt_pk_bf16_f32 v48, v48, v83
	global_store_dword v[80:81], v48, off
.LBB0_531:
	s_or_b64 exec, exec, s[40:41]
	v_mul_f32_e32 v32, v32, v82
	s_nop 1
	v_mov_b32_dpp v48, v32 quad_perm:[1,0,3,2] row_mask:0xf bank_mask:0xf
	s_and_saveexec_b64 s[40:41], s[38:39]
	s_cbranch_execz .LBB0_533
	s_waitcnt lgkmcnt(0)
	v_cvt_pk_bf16_f32 v32, v32, v48
	global_store_dword v[80:81], v32, off offset:64
.LBB0_533:
	s_or_b64 exec, exec, s[40:41]
	v_mul_f32_e32 v16, v16, v82
	s_nop 1
	v_mov_b32_dpp v32, v16 quad_perm:[1,0,3,2] row_mask:0xf bank_mask:0xf
	s_and_saveexec_b64 s[40:41], s[38:39]
	s_cbranch_execz .LBB0_535
	s_waitcnt lgkmcnt(0)
	v_cvt_pk_bf16_f32 v16, v16, v32
	global_store_dword v[80:81], v16, off offset:128
.LBB0_535:
	s_or_b64 exec, exec, s[40:41]
	v_mul_f32_e32 v0, v0, v82
	s_nop 1
	v_mov_b32_dpp v16, v0 quad_perm:[1,0,3,2] row_mask:0xf bank_mask:0xf
	s_and_saveexec_b64 s[40:41], s[38:39]
	s_cbranch_execz .LBB0_537
	s_waitcnt lgkmcnt(0)
	v_cvt_pk_bf16_f32 v0, v0, v16
	global_store_dword v[80:81], v0, off offset:192
.LBB0_537:
	s_or_b64 exec, exec, s[40:41]
	v_rcp_f32_e32 v0, v77
	s_waitcnt lgkmcnt(0)
	v_mul_f32_e32 v16, v49, v0
	s_nop 1
	v_mov_b32_dpp v32, v16 quad_perm:[1,0,3,2] row_mask:0xf bank_mask:0xf
	s_and_saveexec_b64 s[40:41], s[38:39]
	s_cbranch_execz .LBB0_539
	v_add_co_u32_e32 v48, vcc, 0x1000, v80
	s_waitcnt lgkmcnt(0)
	v_cvt_pk_bf16_f32 v16, v16, v32
	s_nop 0
	v_addc_co_u32_e32 v49, vcc, 0, v81, vcc
	global_store_dword v[48:49], v16, off offset:128
.LBB0_539:
	s_or_b64 exec, exec, s[40:41]
	v_mul_f32_e32 v16, v33, v0
	s_waitcnt lgkmcnt(0)
	s_nop 1
	v_mov_b32_dpp v32, v16 quad_perm:[1,0,3,2] row_mask:0xf bank_mask:0xf
	s_and_saveexec_b64 s[40:41], s[38:39]
	s_cbranch_execz .LBB0_541
	s_waitcnt lgkmcnt(0)
	v_cvt_pk_bf16_f32 v16, v16, v32
	v_add_co_u32_e32 v32, vcc, 0x1000, v80
	s_nop 1
	v_addc_co_u32_e32 v33, vcc, 0, v81, vcc
	global_store_dword v[32:33], v16, off offset:192
.LBB0_541:
	s_or_b64 exec, exec, s[40:41]
	v_mul_f32_e32 v16, v17, v0
	s_nop 1
	v_mov_b32_dpp v17, v16 quad_perm:[1,0,3,2] row_mask:0xf bank_mask:0xf
	s_and_saveexec_b64 s[40:41], s[38:39]
	s_cbranch_execz .LBB0_543
	s_waitcnt lgkmcnt(0)
	v_cvt_pk_bf16_f32 v32, v16, v17
	v_add_co_u32_e32 v16, vcc, 0x1000, v80
	s_nop 1
	v_addc_co_u32_e32 v17, vcc, 0, v81, vcc
	global_store_dword v[16:17], v32, off offset:256
.LBB0_543:
	s_or_b64 exec, exec, s[40:41]
	v_mul_f32_e32 v0, v1, v0
	s_nop 1
	v_mov_b32_dpp v1, v0 quad_perm:[1,0,3,2] row_mask:0xf bank_mask:0xf
	s_and_saveexec_b64 s[40:41], s[38:39]
	s_cbranch_execz .LBB0_545
	s_waitcnt lgkmcnt(0)
	v_cvt_pk_bf16_f32 v16, v0, v1
	v_add_co_u32_e32 v0, vcc, 0x1000, v80
	s_nop 1
	v_addc_co_u32_e32 v1, vcc, 0, v81, vcc
	global_store_dword v[0:1], v16, off offset:320
.LBB0_545:
	s_or_b64 exec, exec, s[40:41]
	v_rcp_f32_e32 v0, v78
	s_waitcnt lgkmcnt(0)
	v_mul_f32_e32 v1, v50, v0
	s_nop 1
	v_mov_b32_dpp v16, v1 quad_perm:[1,0,3,2] row_mask:0xf bank_mask:0xf
	s_and_saveexec_b64 s[40:41], s[38:39]
	s_cbranch_execz .LBB0_547
	s_waitcnt lgkmcnt(0)
	v_cvt_pk_bf16_f32 v1, v1, v16
	v_add_co_u32_e32 v16, vcc, 0x2000, v80
	s_nop 1
	v_addc_co_u32_e32 v17, vcc, 0, v81, vcc
	global_store_dword v[16:17], v1, off offset:256
.LBB0_547:
	s_or_b64 exec, exec, s[40:41]
	v_mul_f32_e32 v1, v34, v0
	s_waitcnt lgkmcnt(0)
	s_nop 1
	v_mov_b32_dpp v16, v1 quad_perm:[1,0,3,2] row_mask:0xf bank_mask:0xf
	s_and_saveexec_b64 s[40:41], s[38:39]
	s_cbranch_execz .LBB0_549
	s_waitcnt lgkmcnt(0)
	v_cvt_pk_bf16_f32 v1, v1, v16
	v_add_co_u32_e32 v16, vcc, 0x2000, v80
	s_nop 1
	v_addc_co_u32_e32 v17, vcc, 0, v81, vcc
	global_store_dword v[16:17], v1, off offset:320
.LBB0_549:
	s_or_b64 exec, exec, s[40:41]
	v_mul_f32_e32 v1, v18, v0
	s_waitcnt lgkmcnt(0)
	s_nop 1
	v_mov_b32_dpp v16, v1 quad_perm:[1,0,3,2] row_mask:0xf bank_mask:0xf
	s_and_saveexec_b64 s[40:41], s[38:39]
	s_cbranch_execz .LBB0_551
	s_waitcnt lgkmcnt(0)
	v_cvt_pk_bf16_f32 v1, v1, v16
	v_add_co_u32_e32 v16, vcc, 0x2000, v80
	s_nop 1
	v_addc_co_u32_e32 v17, vcc, 0, v81, vcc
	global_store_dword v[16:17], v1, off offset:384
.LBB0_551:
	s_or_b64 exec, exec, s[40:41]
	v_mul_f32_e32 v0, v2, v0
	s_nop 1
	v_mov_b32_dpp v1, v0 quad_perm:[1,0,3,2] row_mask:0xf bank_mask:0xf
	s_and_saveexec_b64 s[40:41], s[38:39]
	s_cbranch_execz .LBB0_553
	s_waitcnt lgkmcnt(0)
	v_cvt_pk_bf16_f32 v2, v0, v1
	v_add_co_u32_e32 v0, vcc, 0x2000, v80
	s_nop 1
	v_addc_co_u32_e32 v1, vcc, 0, v81, vcc
	global_store_dword v[0:1], v2, off offset:448
.LBB0_553:
	s_or_b64 exec, exec, s[40:41]
	v_rcp_f32_e32 v0, v79
	s_waitcnt lgkmcnt(0)
	v_mul_f32_e32 v1, v51, v0
	s_nop 1
	v_mov_b32_dpp v2, v1 quad_perm:[1,0,3,2] row_mask:0xf bank_mask:0xf
	s_and_saveexec_b64 s[40:41], s[38:39]
	s_cbranch_execz .LBB0_555
	v_add_co_u32_e32 v16, vcc, 0x3000, v80
	s_waitcnt lgkmcnt(0)
	v_cvt_pk_bf16_f32 v1, v1, v2
	s_nop 0
	v_addc_co_u32_e32 v17, vcc, 0, v81, vcc
	global_store_dword v[16:17], v1, off offset:384
.LBB0_555:
	s_or_b64 exec, exec, s[40:41]
	v_mul_f32_e32 v1, v35, v0
	s_waitcnt lgkmcnt(0)
	s_nop 1
	v_mov_b32_dpp v2, v1 quad_perm:[1,0,3,2] row_mask:0xf bank_mask:0xf
	s_and_saveexec_b64 s[40:41], s[38:39]
	s_cbranch_execz .LBB0_557
	v_add_co_u32_e32 v16, vcc, 0x3000, v80
	s_waitcnt lgkmcnt(0)
	v_cvt_pk_bf16_f32 v1, v1, v2
	s_nop 0
	v_addc_co_u32_e32 v17, vcc, 0, v81, vcc
	global_store_dword v[16:17], v1, off offset:448
.LBB0_557:
	s_or_b64 exec, exec, s[40:41]
	v_mul_f32_e32 v1, v19, v0
	s_waitcnt lgkmcnt(0)
	s_nop 1
	v_mov_b32_dpp v2, v1 quad_perm:[1,0,3,2] row_mask:0xf bank_mask:0xf
	s_and_saveexec_b64 s[40:41], s[38:39]
	s_cbranch_execz .LBB0_559
	v_add_co_u32_e32 v16, vcc, 0x3000, v80
	s_waitcnt lgkmcnt(0)
	v_cvt_pk_bf16_f32 v1, v1, v2
	s_nop 0
	v_addc_co_u32_e32 v17, vcc, 0, v81, vcc
	global_store_dword v[16:17], v1, off offset:512
.LBB0_559:
	s_or_b64 exec, exec, s[40:41]
	v_mul_f32_e32 v0, v3, v0
	s_nop 1
	v_mov_b32_dpp v1, v0 quad_perm:[1,0,3,2] row_mask:0xf bank_mask:0xf
	s_and_saveexec_b64 s[40:41], s[38:39]
	s_cbranch_execz .LBB0_561
	s_waitcnt lgkmcnt(0)
	v_cvt_pk_bf16_f32 v2, v0, v1
	v_add_co_u32_e32 v0, vcc, 0x3000, v80
	s_nop 1
	v_addc_co_u32_e32 v1, vcc, 0, v81, vcc
	global_store_dword v[0:1], v2, off offset:576
.LBB0_561:
	s_or_b64 exec, exec, s[40:41]
	v_rcp_f32_e32 v0, v72
	s_waitcnt lgkmcnt(0)
	v_mul_f32_e32 v1, v52, v0
	s_nop 1
	v_mov_b32_dpp v2, v1 quad_perm:[1,0,3,2] row_mask:0xf bank_mask:0xf
	s_and_saveexec_b64 s[40:41], s[38:39]
	s_cbranch_execz .LBB0_563
	s_waitcnt lgkmcnt(0)
	v_cvt_pk_bf16_f32 v1, v1, v2
	v_add_co_u32_e32 v2, vcc, 0x8000, v80
	s_nop 1
	v_addc_co_u32_e32 v3, vcc, 0, v81, vcc
	global_store_dword v[2:3], v1, off offset:1024
.LBB0_563:
	s_or_b64 exec, exec, s[40:41]
	v_mul_f32_e32 v1, v36, v0
	s_waitcnt lgkmcnt(0)
	s_nop 1
	v_mov_b32_dpp v2, v1 quad_perm:[1,0,3,2] row_mask:0xf bank_mask:0xf
	s_and_saveexec_b64 s[40:41], s[38:39]
	s_cbranch_execz .LBB0_565
	s_waitcnt lgkmcnt(0)
	v_cvt_pk_bf16_f32 v1, v1, v2
	v_add_co_u32_e32 v2, vcc, 0x8000, v80
	s_nop 1
	v_addc_co_u32_e32 v3, vcc, 0, v81, vcc
	global_store_dword v[2:3], v1, off offset:1088
.LBB0_565:
	s_or_b64 exec, exec, s[40:41]
	v_mul_f32_e32 v1, v20, v0
	s_waitcnt lgkmcnt(0)
	s_nop 1
	v_mov_b32_dpp v2, v1 quad_perm:[1,0,3,2] row_mask:0xf bank_mask:0xf
	s_and_saveexec_b64 s[40:41], s[38:39]
	s_cbranch_execz .LBB0_567
	s_waitcnt lgkmcnt(0)
	v_cvt_pk_bf16_f32 v1, v1, v2
	v_add_co_u32_e32 v2, vcc, 0x8000, v80
	s_nop 1
	v_addc_co_u32_e32 v3, vcc, 0, v81, vcc
	global_store_dword v[2:3], v1, off offset:1152
.LBB0_567:
	s_or_b64 exec, exec, s[40:41]
	v_mul_f32_e32 v0, v4, v0
	s_nop 1
	v_mov_b32_dpp v1, v0 quad_perm:[1,0,3,2] row_mask:0xf bank_mask:0xf
	s_and_saveexec_b64 s[40:41], s[38:39]
	s_cbranch_execz .LBB0_569
	s_waitcnt lgkmcnt(0)
	v_cvt_pk_bf16_f32 v2, v0, v1
	v_add_co_u32_e32 v0, vcc, 0x8000, v80
	s_nop 1
	v_addc_co_u32_e32 v1, vcc, 0, v81, vcc
	global_store_dword v[0:1], v2, off offset:1216
.LBB0_569:
	s_or_b64 exec, exec, s[40:41]
	v_rcp_f32_e32 v0, v73
	s_waitcnt lgkmcnt(0)
	v_mul_f32_e32 v1, v53, v0
	s_nop 1
	v_mov_b32_dpp v2, v1 quad_perm:[1,0,3,2] row_mask:0xf bank_mask:0xf
	s_and_saveexec_b64 s[40:41], s[38:39]
	s_cbranch_execz .LBB0_571
	s_waitcnt lgkmcnt(0)
	v_cvt_pk_bf16_f32 v1, v1, v2
	v_add_co_u32_e32 v2, vcc, 0x9000, v80
	s_nop 1
	v_addc_co_u32_e32 v3, vcc, 0, v81, vcc
	global_store_dword v[2:3], v1, off offset:1152
.LBB0_571:
	s_or_b64 exec, exec, s[40:41]
	v_mul_f32_e32 v1, v37, v0
	s_waitcnt lgkmcnt(0)
	s_nop 1
	v_mov_b32_dpp v2, v1 quad_perm:[1,0,3,2] row_mask:0xf bank_mask:0xf
	s_and_saveexec_b64 s[40:41], s[38:39]
	s_cbranch_execz .LBB0_573
	s_waitcnt lgkmcnt(0)
	v_cvt_pk_bf16_f32 v1, v1, v2
	v_add_co_u32_e32 v2, vcc, 0x9000, v80
	s_nop 1
	v_addc_co_u32_e32 v3, vcc, 0, v81, vcc
	global_store_dword v[2:3], v1, off offset:1216
.LBB0_573:
	s_or_b64 exec, exec, s[40:41]
	v_mul_f32_e32 v1, v21, v0
	s_waitcnt lgkmcnt(0)
	s_nop 1
	v_mov_b32_dpp v2, v1 quad_perm:[1,0,3,2] row_mask:0xf bank_mask:0xf
	s_and_saveexec_b64 s[40:41], s[38:39]
	s_cbranch_execz .LBB0_575
	s_waitcnt lgkmcnt(0)
	v_cvt_pk_bf16_f32 v1, v1, v2
	v_add_co_u32_e32 v2, vcc, 0x9000, v80
	s_nop 1
	v_addc_co_u32_e32 v3, vcc, 0, v81, vcc
	global_store_dword v[2:3], v1, off offset:1280
.LBB0_575:
	s_or_b64 exec, exec, s[40:41]
	v_mul_f32_e32 v0, v5, v0
	s_nop 1
	v_mov_b32_dpp v1, v0 quad_perm:[1,0,3,2] row_mask:0xf bank_mask:0xf
	s_and_saveexec_b64 s[40:41], s[38:39]
	s_cbranch_execz .LBB0_577
	s_waitcnt lgkmcnt(0)
	v_cvt_pk_bf16_f32 v2, v0, v1
	v_add_co_u32_e32 v0, vcc, 0x9000, v80
	s_nop 1
	v_addc_co_u32_e32 v1, vcc, 0, v81, vcc
	global_store_dword v[0:1], v2, off offset:1344
.LBB0_577:
	s_or_b64 exec, exec, s[40:41]
	v_rcp_f32_e32 v0, v74
	s_waitcnt lgkmcnt(0)
	v_mul_f32_e32 v1, v54, v0
	s_nop 1
	v_mov_b32_dpp v2, v1 quad_perm:[1,0,3,2] row_mask:0xf bank_mask:0xf
	s_and_saveexec_b64 s[40:41], s[38:39]
	s_cbranch_execz .LBB0_579
	s_waitcnt lgkmcnt(0)
	v_cvt_pk_bf16_f32 v1, v1, v2
	v_add_co_u32_e32 v2, vcc, 0xa000, v80
	s_nop 1
	v_addc_co_u32_e32 v3, vcc, 0, v81, vcc
	global_store_dword v[2:3], v1, off offset:1280
; __device__ __forceinline__ unsigned cvt_pk_bf16(float lo, float hi) { unsigned r; asm volatile("v_cvt_pk_bf16_f32 %0, %1, %2" : "=v"(r) : "v"(lo), "v"(hi)); return r; }
; __device__ __forceinline__ int crow(int r, int hi) { return (r & 3) + 8 * (r >> 2) + 4 * hi; }
; __device__ __forceinline__ void causal_block(const BlockRef& cur, const BlockRef& nxt, int skv, int W, char* lds, Seam& S) {
;     ...
;     for (int r = 0; r < 16; ++r) { const int orow = crow(r, hi);
; #pragma unroll
;         for (int d0 = 0; d0 < 4; ++d0) { const float v = o[d0][r] * rli[r];
;             const float vn = __shfl_xor(v, 1);
;             if ((r32 & 1) == 0) *(unsigned*)(Ow + (size_t)orow * OSTR + d0 * 32 + r32) = cvt_pk_bf16(v, vn); } }
.LBB0_579:
	s_or_b64 exec, exec, s[40:41]
	v_mul_f32_e32 v1, v38, v0
	s_waitcnt lgkmcnt(0)
	s_nop 1
	v_mov_b32_dpp v2, v1 quad_perm:[1,0,3,2] row_mask:0xf bank_mask:0xf
	s_and_saveexec_b64 s[40:41], s[38:39]
	s_cbranch_execz .LBB0_581
	s_waitcnt lgkmcnt(0)
	v_cvt_pk_bf16_f32 v1, v1, v2
	v_add_co_u32_e32 v2, vcc, 0xa000, v80
	s_nop 1
	v_addc_co_u32_e32 v3, vcc, 0, v81, vcc
	global_store_dword v[2:3], v1, off offset:1344
.LBB0_581:
	s_or_b64 exec, exec, s[40:41]
	v_mul_f32_e32 v1, v22, v0
	s_waitcnt lgkmcnt(0)
	s_nop 1
	v_mov_b32_dpp v2, v1 quad_perm:[1,0,3,2] row_mask:0xf bank_mask:0xf
	s_and_saveexec_b64 s[40:41], s[38:39]
	s_cbranch_execz .LBB0_583
	s_waitcnt lgkmcnt(0)
	v_cvt_pk_bf16_f32 v1, v1, v2
	v_add_co_u32_e32 v2, vcc, 0xa000, v80
	s_nop 1
	v_addc_co_u32_e32 v3, vcc, 0, v81, vcc
	global_store_dword v[2:3], v1, off offset:1408
.LBB0_583:
	s_or_b64 exec, exec, s[40:41]
	v_mul_f32_e32 v0, v6, v0
	s_nop 1
	v_mov_b32_dpp v1, v0 quad_perm:[1,0,3,2] row_mask:0xf bank_mask:0xf
	s_and_saveexec_b64 s[40:41], s[38:39]
	s_cbranch_execz .LBB0_585
	s_waitcnt lgkmcnt(0)
	v_cvt_pk_bf16_f32 v2, v0, v1
	v_add_co_u32_e32 v0, vcc, 0xa000, v80
	s_nop 1
	v_addc_co_u32_e32 v1, vcc, 0, v81, vcc
	global_store_dword v[0:1], v2, off offset:1472
.LBB0_585:
	s_or_b64 exec, exec, s[40:41]
	v_rcp_f32_e32 v0, v75
	s_waitcnt lgkmcnt(0)
	v_mul_f32_e32 v1, v55, v0
	s_nop 1
	v_mov_b32_dpp v2, v1 quad_perm:[1,0,3,2] row_mask:0xf bank_mask:0xf
	s_and_saveexec_b64 s[40:41], s[38:39]
	s_cbranch_execz .LBB0_587
	s_waitcnt lgkmcnt(0)
	v_cvt_pk_bf16_f32 v1, v1, v2
	v_add_co_u32_e32 v2, vcc, 0xb000, v80
	s_nop 1
	v_addc_co_u32_e32 v3, vcc, 0, v81, vcc
	global_store_dword v[2:3], v1, off offset:1408
.LBB0_587:
	s_or_b64 exec, exec, s[40:41]
	v_mul_f32_e32 v1, v39, v0
	s_waitcnt lgkmcnt(0)
	s_nop 1
	v_mov_b32_dpp v2, v1 quad_perm:[1,0,3,2] row_mask:0xf bank_mask:0xf
	s_and_saveexec_b64 s[40:41], s[38:39]
	s_cbranch_execz .LBB0_589
	s_waitcnt lgkmcnt(0)
	v_cvt_pk_bf16_f32 v1, v1, v2
	v_add_co_u32_e32 v2, vcc, 0xb000, v80
	s_nop 1
	v_addc_co_u32_e32 v3, vcc, 0, v81, vcc
	global_store_dword v[2:3], v1, off offset:1472
.LBB0_589:
	s_or_b64 exec, exec, s[40:41]
	v_mul_f32_e32 v1, v23, v0
	s_waitcnt lgkmcnt(0)
	s_nop 1
	v_mov_b32_dpp v2, v1 quad_perm:[1,0,3,2] row_mask:0xf bank_mask:0xf
	s_and_saveexec_b64 s[40:41], s[38:39]
	s_cbranch_execz .LBB0_591
	s_waitcnt lgkmcnt(0)
	v_cvt_pk_bf16_f32 v1, v1, v2
	v_add_co_u32_e32 v2, vcc, 0xb000, v80
	s_nop 1
	v_addc_co_u32_e32 v3, vcc, 0, v81, vcc
	global_store_dword v[2:3], v1, off offset:1536
.LBB0_591:
	s_or_b64 exec, exec, s[40:41]
	v_mul_f32_e32 v0, v7, v0
	s_nop 1
	v_mov_b32_dpp v1, v0 quad_perm:[1,0,3,2] row_mask:0xf bank_mask:0xf
	s_and_saveexec_b64 s[40:41], s[38:39]
	s_cbranch_execz .LBB0_593
	s_waitcnt lgkmcnt(0)
	v_cvt_pk_bf16_f32 v2, v0, v1
	v_add_co_u32_e32 v0, vcc, 0xb000, v80
	s_nop 1
	v_addc_co_u32_e32 v1, vcc, 0, v81, vcc
	global_store_dword v[0:1], v2, off offset:1600
.LBB0_593:
	s_or_b64 exec, exec, s[40:41]
	v_rcp_f32_e32 v0, v68
	s_waitcnt lgkmcnt(0)
	v_mul_f32_e32 v1, v56, v0
	s_nop 1
	v_mov_b32_dpp v2, v1 quad_perm:[1,0,3,2] row_mask:0xf bank_mask:0xf
	s_and_saveexec_b64 s[40:41], s[38:39]
	s_cbranch_execz .LBB0_595
	s_waitcnt lgkmcnt(0)
	v_cvt_pk_bf16_f32 v1, v1, v2
	v_add_co_u32_e32 v2, vcc, 0x10000, v80
	s_nop 1
	v_addc_co_u32_e32 v3, vcc, 0, v81, vcc
	global_store_dword v[2:3], v1, off offset:2048
.LBB0_595:
	s_or_b64 exec, exec, s[40:41]
	v_mul_f32_e32 v1, v40, v0
	s_waitcnt lgkmcnt(0)
	s_nop 1
	v_mov_b32_dpp v2, v1 quad_perm:[1,0,3,2] row_mask:0xf bank_mask:0xf
	s_and_saveexec_b64 s[40:41], s[38:39]
	s_cbranch_execz .LBB0_597
	s_waitcnt lgkmcnt(0)
	v_cvt_pk_bf16_f32 v1, v1, v2
	v_add_co_u32_e32 v2, vcc, 0x10000, v80
	s_nop 1
	v_addc_co_u32_e32 v3, vcc, 0, v81, vcc
	global_store_dword v[2:3], v1, off offset:2112
.LBB0_597:
	s_or_b64 exec, exec, s[40:41]
	v_mul_f32_e32 v1, v24, v0
	s_waitcnt lgkmcnt(0)
	s_nop 1
	v_mov_b32_dpp v2, v1 quad_perm:[1,0,3,2] row_mask:0xf bank_mask:0xf
	s_and_saveexec_b64 s[40:41], s[38:39]
	s_cbranch_execz .LBB0_599
	s_waitcnt lgkmcnt(0)
	v_cvt_pk_bf16_f32 v1, v1, v2
	v_add_co_u32_e32 v2, vcc, 0x10000, v80
	s_nop 1
	v_addc_co_u32_e32 v3, vcc, 0, v81, vcc
	global_store_dword v[2:3], v1, off offset:2176
.LBB0_599:
	s_or_b64 exec, exec, s[40:41]
	v_mul_f32_e32 v0, v8, v0
	s_nop 1
	v_mov_b32_dpp v1, v0 quad_perm:[1,0,3,2] row_mask:0xf bank_mask:0xf
	s_and_saveexec_b64 s[40:41], s[38:39]
	s_cbranch_execz .LBB0_601
	s_waitcnt lgkmcnt(0)
	v_cvt_pk_bf16_f32 v2, v0, v1
	v_add_co_u32_e32 v0, vcc, 0x10000, v80
	s_nop 1
	v_addc_co_u32_e32 v1, vcc, 0, v81, vcc
	global_store_dword v[0:1], v2, off offset:2240
.LBB0_601:
	s_or_b64 exec, exec, s[40:41]
	v_rcp_f32_e32 v0, v69
	s_waitcnt lgkmcnt(0)
	v_mul_f32_e32 v1, v57, v0
	s_nop 1
	v_mov_b32_dpp v2, v1 quad_perm:[1,0,3,2] row_mask:0xf bank_mask:0xf
	s_and_saveexec_b64 s[40:41], s[38:39]
	s_cbranch_execz .LBB0_603
	s_waitcnt lgkmcnt(0)
	v_cvt_pk_bf16_f32 v1, v1, v2
	v_add_co_u32_e32 v2, vcc, 0x11000, v80
	s_nop 1
	v_addc_co_u32_e32 v3, vcc, 0, v81, vcc
	global_store_dword v[2:3], v1, off offset:2176
.LBB0_603:
	s_or_b64 exec, exec, s[40:41]
	v_mul_f32_e32 v1, v41, v0
	s_waitcnt lgkmcnt(0)
	s_nop 1
	v_mov_b32_dpp v2, v1 quad_perm:[1,0,3,2] row_mask:0xf bank_mask:0xf
	s_and_saveexec_b64 s[40:41], s[38:39]
	s_cbranch_execz .LBB0_605
	s_waitcnt lgkmcnt(0)
	v_cvt_pk_bf16_f32 v1, v1, v2
	v_add_co_u32_e32 v2, vcc, 0x11000, v80
	s_nop 1
	v_addc_co_u32_e32 v3, vcc, 0, v81, vcc
	global_store_dword v[2:3], v1, off offset:2240
; __device__ __forceinline__ unsigned cvt_pk_bf16(float lo, float hi) { unsigned r; asm volatile("v_cvt_pk_bf16_f32 %0, %1, %2" : "=v"(r) : "v"(lo), "v"(hi)); return r; }
; __device__ __forceinline__ int crow(int r, int hi) { return (r & 3) + 8 * (r >> 2) + 4 * hi; }
; __device__ __forceinline__ void causal_block(const BlockRef& cur, const BlockRef& nxt, int skv, int W, char* lds, Seam& S) {
;     ...
;     for (int r = 0; r < 16; ++r) { const int orow = crow(r, hi);
; #pragma unroll
;         for (int d0 = 0; d0 < 4; ++d0) { const float v = o[d0][r] * rli[r];
;             const float vn = __shfl_xor(v, 1);
;             if ((r32 & 1) == 0) *(unsigned*)(Ow + (size_t)orow * OSTR + d0 * 32 + r32) = cvt_pk_bf16(v, vn); } }
.LBB0_605:
	s_or_b64 exec, exec, s[40:41]
	v_mul_f32_e32 v1, v25, v0
	s_waitcnt lgkmcnt(0)
	s_nop 1
	v_mov_b32_dpp v2, v1 quad_perm:[1,0,3,2] row_mask:0xf bank_mask:0xf
	s_and_saveexec_b64 s[40:41], s[38:39]
	s_cbranch_execz .LBB0_607
	s_waitcnt lgkmcnt(0)
	v_cvt_pk_bf16_f32 v1, v1, v2
	v_add_co_u32_e32 v2, vcc, 0x11000, v80
	s_nop 1
	v_addc_co_u32_e32 v3, vcc, 0, v81, vcc
	global_store_dword v[2:3], v1, off offset:2304
.LBB0_607:
	s_or_b64 exec, exec, s[40:41]
	v_mul_f32_e32 v0, v9, v0
	s_nop 1
	v_mov_b32_dpp v1, v0 quad_perm:[1,0,3,2] row_mask:0xf bank_mask:0xf
	s_and_saveexec_b64 s[40:41], s[38:39]
	s_cbranch_execz .LBB0_609
	s_waitcnt lgkmcnt(0)
	v_cvt_pk_bf16_f32 v2, v0, v1
	v_add_co_u32_e32 v0, vcc, 0x11000, v80
	s_nop 1
	v_addc_co_u32_e32 v1, vcc, 0, v81, vcc
	global_store_dword v[0:1], v2, off offset:2368
.LBB0_609:
	s_or_b64 exec, exec, s[40:41]
	v_rcp_f32_e32 v0, v70
	s_waitcnt lgkmcnt(0)
	v_mul_f32_e32 v1, v58, v0
	s_nop 1
	v_mov_b32_dpp v2, v1 quad_perm:[1,0,3,2] row_mask:0xf bank_mask:0xf
	s_and_saveexec_b64 s[40:41], s[38:39]
	s_cbranch_execz .LBB0_611
	s_waitcnt lgkmcnt(0)
	v_cvt_pk_bf16_f32 v1, v1, v2
	v_add_co_u32_e32 v2, vcc, 0x12000, v80
	s_nop 1
	v_addc_co_u32_e32 v3, vcc, 0, v81, vcc
	global_store_dword v[2:3], v1, off offset:2304
.LBB0_611:
	s_or_b64 exec, exec, s[40:41]
	v_mul_f32_e32 v1, v42, v0
	s_waitcnt lgkmcnt(0)
	s_nop 1
	v_mov_b32_dpp v2, v1 quad_perm:[1,0,3,2] row_mask:0xf bank_mask:0xf
	s_and_saveexec_b64 s[40:41], s[38:39]
	s_cbranch_execz .LBB0_613
	s_waitcnt lgkmcnt(0)
	v_cvt_pk_bf16_f32 v1, v1, v2
	v_add_co_u32_e32 v2, vcc, 0x12000, v80
	s_nop 1
	v_addc_co_u32_e32 v3, vcc, 0, v81, vcc
	global_store_dword v[2:3], v1, off offset:2368
.LBB0_613:
	s_or_b64 exec, exec, s[40:41]
	v_mul_f32_e32 v1, v26, v0
	s_waitcnt lgkmcnt(0)
	s_nop 1
	v_mov_b32_dpp v2, v1 quad_perm:[1,0,3,2] row_mask:0xf bank_mask:0xf
	s_and_saveexec_b64 s[40:41], s[38:39]
	s_cbranch_execz .LBB0_615
	s_waitcnt lgkmcnt(0)
	v_cvt_pk_bf16_f32 v1, v1, v2
	v_add_co_u32_e32 v2, vcc, 0x12000, v80
	s_nop 1
	v_addc_co_u32_e32 v3, vcc, 0, v81, vcc
	global_store_dword v[2:3], v1, off offset:2432
.LBB0_615:
	s_or_b64 exec, exec, s[40:41]
	v_mul_f32_e32 v0, v10, v0
	s_nop 1
	v_mov_b32_dpp v1, v0 quad_perm:[1,0,3,2] row_mask:0xf bank_mask:0xf
	s_and_saveexec_b64 s[40:41], s[38:39]
	s_cbranch_execz .LBB0_617
	s_waitcnt lgkmcnt(0)
	v_cvt_pk_bf16_f32 v2, v0, v1
	v_add_co_u32_e32 v0, vcc, 0x12000, v80
	s_nop 1
	v_addc_co_u32_e32 v1, vcc, 0, v81, vcc
	global_store_dword v[0:1], v2, off offset:2496
.LBB0_617:
	s_or_b64 exec, exec, s[40:41]
	v_rcp_f32_e32 v0, v71
	s_waitcnt lgkmcnt(0)
	v_mul_f32_e32 v1, v59, v0
	s_nop 1
	v_mov_b32_dpp v2, v1 quad_perm:[1,0,3,2] row_mask:0xf bank_mask:0xf
	s_and_saveexec_b64 s[40:41], s[38:39]
	s_cbranch_execz .LBB0_619
	s_waitcnt lgkmcnt(0)
	v_cvt_pk_bf16_f32 v1, v1, v2
	v_add_co_u32_e32 v2, vcc, 0x13000, v80
	s_nop 1
	v_addc_co_u32_e32 v3, vcc, 0, v81, vcc
	global_store_dword v[2:3], v1, off offset:2432
.LBB0_619:
	s_or_b64 exec, exec, s[40:41]
	v_mul_f32_e32 v1, v43, v0
	s_waitcnt lgkmcnt(0)
	s_nop 1
	v_mov_b32_dpp v2, v1 quad_perm:[1,0,3,2] row_mask:0xf bank_mask:0xf
	s_and_saveexec_b64 s[40:41], s[38:39]
	s_cbranch_execz .LBB0_621
	s_waitcnt lgkmcnt(0)
	v_cvt_pk_bf16_f32 v1, v1, v2
	v_add_co_u32_e32 v2, vcc, 0x13000, v80
	s_nop 1
	v_addc_co_u32_e32 v3, vcc, 0, v81, vcc
	global_store_dword v[2:3], v1, off offset:2496
.LBB0_621:
	s_or_b64 exec, exec, s[40:41]
	v_mul_f32_e32 v1, v27, v0
	s_waitcnt lgkmcnt(0)
	s_nop 1
	v_mov_b32_dpp v2, v1 quad_perm:[1,0,3,2] row_mask:0xf bank_mask:0xf
	s_and_saveexec_b64 s[40:41], s[38:39]
	s_cbranch_execz .LBB0_623
	s_waitcnt lgkmcnt(0)
	v_cvt_pk_bf16_f32 v1, v1, v2
	v_add_co_u32_e32 v2, vcc, 0x13000, v80
	s_nop 1
	v_addc_co_u32_e32 v3, vcc, 0, v81, vcc
	global_store_dword v[2:3], v1, off offset:2560
.LBB0_623:
	s_or_b64 exec, exec, s[40:41]
	v_mul_f32_e32 v0, v11, v0
	s_nop 1
	v_mov_b32_dpp v1, v0 quad_perm:[1,0,3,2] row_mask:0xf bank_mask:0xf
	s_and_saveexec_b64 s[40:41], s[38:39]
	s_cbranch_execz .LBB0_625
	s_waitcnt lgkmcnt(0)
	v_cvt_pk_bf16_f32 v2, v0, v1
	v_add_co_u32_e32 v0, vcc, 0x13000, v80
	s_nop 1
	v_addc_co_u32_e32 v1, vcc, 0, v81, vcc
	global_store_dword v[0:1], v2, off offset:2624
.LBB0_625:
	s_or_b64 exec, exec, s[40:41]
	v_rcp_f32_e32 v0, v64
	s_waitcnt lgkmcnt(0)
	v_mul_f32_e32 v1, v60, v0
	s_nop 1
	v_mov_b32_dpp v2, v1 quad_perm:[1,0,3,2] row_mask:0xf bank_mask:0xf
	s_and_saveexec_b64 s[40:41], s[38:39]
	s_cbranch_execz .LBB0_627
	s_waitcnt lgkmcnt(0)
	v_cvt_pk_bf16_f32 v1, v1, v2
	v_add_co_u32_e32 v2, vcc, 0x18000, v80
	s_nop 1
	v_addc_co_u32_e32 v3, vcc, 0, v81, vcc
	global_store_dword v[2:3], v1, off offset:3072
.LBB0_627:
	s_or_b64 exec, exec, s[40:41]
	v_mul_f32_e32 v1, v44, v0
	s_waitcnt lgkmcnt(0)
	s_nop 1
	v_mov_b32_dpp v2, v1 quad_perm:[1,0,3,2] row_mask:0xf bank_mask:0xf
	s_and_saveexec_b64 s[40:41], s[38:39]
	s_cbranch_execz .LBB0_629
	s_waitcnt lgkmcnt(0)
	v_cvt_pk_bf16_f32 v1, v1, v2
	v_add_co_u32_e32 v2, vcc, 0x18000, v80
	s_nop 1
	v_addc_co_u32_e32 v3, vcc, 0, v81, vcc
	global_store_dword v[2:3], v1, off offset:3136
.LBB0_629:
	s_or_b64 exec, exec, s[40:41]
	v_mul_f32_e32 v1, v28, v0
	s_waitcnt lgkmcnt(0)
	s_nop 1
	v_mov_b32_dpp v2, v1 quad_perm:[1,0,3,2] row_mask:0xf bank_mask:0xf
	s_and_saveexec_b64 s[40:41], s[38:39]
	s_cbranch_execz .LBB0_631
	s_waitcnt lgkmcnt(0)
	v_cvt_pk_bf16_f32 v1, v1, v2
	v_add_co_u32_e32 v2, vcc, 0x18000, v80
	s_nop 1
	v_addc_co_u32_e32 v3, vcc, 0, v81, vcc
	global_store_dword v[2:3], v1, off offset:3200
; __device__ __forceinline__ unsigned cvt_pk_bf16(float lo, float hi) { unsigned r; asm volatile("v_cvt_pk_bf16_f32 %0, %1, %2" : "=v"(r) : "v"(lo), "v"(hi)); return r; }
; __device__ __forceinline__ int crow(int r, int hi) { return (r & 3) + 8 * (r >> 2) + 4 * hi; }
; __device__ __forceinline__ void causal_block(const BlockRef& cur, const BlockRef& nxt, int skv, int W, char* lds, Seam& S) {
;     ...
;     for (int r = 0; r < 16; ++r) { const int orow = crow(r, hi);
; #pragma unroll
;         for (int d0 = 0; d0 < 4; ++d0) { const float v = o[d0][r] * rli[r];
;             const float vn = __shfl_xor(v, 1);
;             if ((r32 & 1) == 0) *(unsigned*)(Ow + (size_t)orow * OSTR + d0 * 32 + r32) = cvt_pk_bf16(v, vn); } }
.LBB0_631:
	s_or_b64 exec, exec, s[40:41]
	v_mul_f32_e32 v0, v12, v0
	s_nop 1
	v_mov_b32_dpp v1, v0 quad_perm:[1,0,3,2] row_mask:0xf bank_mask:0xf
	s_and_saveexec_b64 s[40:41], s[38:39]
	s_cbranch_execz .LBB0_633
	s_waitcnt lgkmcnt(0)
	v_cvt_pk_bf16_f32 v2, v0, v1
	v_add_co_u32_e32 v0, vcc, 0x18000, v80
	s_nop 1
	v_addc_co_u32_e32 v1, vcc, 0, v81, vcc
	global_store_dword v[0:1], v2, off offset:3264
.LBB0_633:
	s_or_b64 exec, exec, s[40:41]
	v_rcp_f32_e32 v0, v65
	s_waitcnt lgkmcnt(0)
	v_mul_f32_e32 v1, v61, v0
	s_nop 1
	v_mov_b32_dpp v2, v1 quad_perm:[1,0,3,2] row_mask:0xf bank_mask:0xf
	s_and_saveexec_b64 s[40:41], s[38:39]
	s_cbranch_execz .LBB0_635
	s_waitcnt lgkmcnt(0)
	v_cvt_pk_bf16_f32 v1, v1, v2
	v_add_co_u32_e32 v2, vcc, 0x19000, v80
	s_nop 1
	v_addc_co_u32_e32 v3, vcc, 0, v81, vcc
	global_store_dword v[2:3], v1, off offset:3200
.LBB0_635:
	s_or_b64 exec, exec, s[40:41]
	v_mul_f32_e32 v1, v45, v0
	s_waitcnt lgkmcnt(0)
	s_nop 1
	v_mov_b32_dpp v2, v1 quad_perm:[1,0,3,2] row_mask:0xf bank_mask:0xf
	s_and_saveexec_b64 s[40:41], s[38:39]
	s_cbranch_execz .LBB0_637
	s_waitcnt lgkmcnt(0)
	v_cvt_pk_bf16_f32 v1, v1, v2
	v_add_co_u32_e32 v2, vcc, 0x19000, v80
	s_nop 1
	v_addc_co_u32_e32 v3, vcc, 0, v81, vcc
	global_store_dword v[2:3], v1, off offset:3264
.LBB0_637:
	s_or_b64 exec, exec, s[40:41]
	v_mul_f32_e32 v1, v29, v0
	s_waitcnt lgkmcnt(0)
	s_nop 1
	v_mov_b32_dpp v2, v1 quad_perm:[1,0,3,2] row_mask:0xf bank_mask:0xf
	s_and_saveexec_b64 s[40:41], s[38:39]
	s_cbranch_execz .LBB0_639
	s_waitcnt lgkmcnt(0)
	v_cvt_pk_bf16_f32 v1, v1, v2
	v_add_co_u32_e32 v2, vcc, 0x19000, v80
	s_nop 1
	v_addc_co_u32_e32 v3, vcc, 0, v81, vcc
	global_store_dword v[2:3], v1, off offset:3328
.LBB0_639:
	s_or_b64 exec, exec, s[40:41]
	v_mul_f32_e32 v0, v13, v0
	s_nop 1
	v_mov_b32_dpp v1, v0 quad_perm:[1,0,3,2] row_mask:0xf bank_mask:0xf
	s_and_saveexec_b64 s[40:41], s[38:39]
	s_cbranch_execz .LBB0_641
	s_waitcnt lgkmcnt(0)
	v_cvt_pk_bf16_f32 v2, v0, v1
	v_add_co_u32_e32 v0, vcc, 0x19000, v80
	s_nop 1
	v_addc_co_u32_e32 v1, vcc, 0, v81, vcc
	global_store_dword v[0:1], v2, off offset:3392
.LBB0_641:
	s_or_b64 exec, exec, s[40:41]
	v_rcp_f32_e32 v0, v66
	s_waitcnt lgkmcnt(0)
	v_mul_f32_e32 v1, v62, v0
	s_nop 1
	v_mov_b32_dpp v2, v1 quad_perm:[1,0,3,2] row_mask:0xf bank_mask:0xf
	s_and_saveexec_b64 s[40:41], s[38:39]
	s_cbranch_execz .LBB0_643
	s_waitcnt lgkmcnt(0)
	v_cvt_pk_bf16_f32 v1, v1, v2
	v_add_co_u32_e32 v2, vcc, 0x1a000, v80
	s_nop 1
	v_addc_co_u32_e32 v3, vcc, 0, v81, vcc
	global_store_dword v[2:3], v1, off offset:3328
.LBB0_643:
	s_or_b64 exec, exec, s[40:41]
	v_mul_f32_e32 v1, v46, v0
	s_waitcnt lgkmcnt(0)
	s_nop 1
	v_mov_b32_dpp v2, v1 quad_perm:[1,0,3,2] row_mask:0xf bank_mask:0xf
	s_and_saveexec_b64 s[40:41], s[38:39]
	s_cbranch_execz .LBB0_645
	s_waitcnt lgkmcnt(0)
	v_cvt_pk_bf16_f32 v1, v1, v2
	v_add_co_u32_e32 v2, vcc, 0x1a000, v80
	s_nop 1
	v_addc_co_u32_e32 v3, vcc, 0, v81, vcc
	global_store_dword v[2:3], v1, off offset:3392
.LBB0_645:
	s_or_b64 exec, exec, s[40:41]
	v_mul_f32_e32 v1, v30, v0
	s_waitcnt lgkmcnt(0)
	s_nop 1
	v_mov_b32_dpp v2, v1 quad_perm:[1,0,3,2] row_mask:0xf bank_mask:0xf
	s_and_saveexec_b64 s[40:41], s[38:39]
	s_cbranch_execz .LBB0_647
	s_waitcnt lgkmcnt(0)
	v_cvt_pk_bf16_f32 v1, v1, v2
	v_add_co_u32_e32 v2, vcc, 0x1a000, v80
	s_nop 1
	v_addc_co_u32_e32 v3, vcc, 0, v81, vcc
	global_store_dword v[2:3], v1, off offset:3456
.LBB0_647:
	s_or_b64 exec, exec, s[40:41]
	v_mul_f32_e32 v0, v14, v0
	s_nop 1
	v_mov_b32_dpp v1, v0 quad_perm:[1,0,3,2] row_mask:0xf bank_mask:0xf
	s_and_saveexec_b64 s[40:41], s[38:39]
	s_cbranch_execz .LBB0_649
	s_waitcnt lgkmcnt(0)
	v_cvt_pk_bf16_f32 v2, v0, v1
	v_add_co_u32_e32 v0, vcc, 0x1a000, v80
	s_nop 1
	v_addc_co_u32_e32 v1, vcc, 0, v81, vcc
	global_store_dword v[0:1], v2, off offset:3520
.LBB0_649:
	s_or_b64 exec, exec, s[40:41]
	v_rcp_f32_e32 v0, v67
	s_waitcnt lgkmcnt(0)
	v_mul_f32_e32 v1, v63, v0
	s_nop 1
	v_mov_b32_dpp v2, v1 quad_perm:[1,0,3,2] row_mask:0xf bank_mask:0xf
	s_and_saveexec_b64 s[40:41], s[38:39]
	s_cbranch_execz .LBB0_651
	s_waitcnt lgkmcnt(0)
	v_cvt_pk_bf16_f32 v1, v1, v2
	v_add_co_u32_e32 v2, vcc, 0x1b000, v80
	s_nop 1
	v_addc_co_u32_e32 v3, vcc, 0, v81, vcc
	global_store_dword v[2:3], v1, off offset:3456
.LBB0_651:
	s_or_b64 exec, exec, s[40:41]
	v_mul_f32_e32 v1, v47, v0
	s_waitcnt lgkmcnt(0)
	s_nop 1
	v_mov_b32_dpp v2, v1 quad_perm:[1,0,3,2] row_mask:0xf bank_mask:0xf
	s_and_saveexec_b64 s[40:41], s[38:39]
	s_cbranch_execz .LBB0_653
	s_waitcnt lgkmcnt(0)
	v_cvt_pk_bf16_f32 v1, v1, v2
	v_add_co_u32_e32 v2, vcc, 0x1b000, v80
	s_nop 1
	v_addc_co_u32_e32 v3, vcc, 0, v81, vcc
	global_store_dword v[2:3], v1, off offset:3520
.LBB0_653:
	s_or_b64 exec, exec, s[40:41]
	v_mul_f32_e32 v1, v31, v0
	s_waitcnt lgkmcnt(0)
	s_nop 1
	v_mov_b32_dpp v2, v1 quad_perm:[1,0,3,2] row_mask:0xf bank_mask:0xf
	s_and_saveexec_b64 s[40:41], s[38:39]
	s_cbranch_execz .LBB0_655
	s_waitcnt lgkmcnt(0)
	v_cvt_pk_bf16_f32 v1, v1, v2
	v_add_co_u32_e32 v2, vcc, 0x1b000, v80
	s_nop 1
	v_addc_co_u32_e32 v3, vcc, 0, v81, vcc
	global_store_dword v[2:3], v1, off offset:3584
.LBB0_655:
	s_or_b64 exec, exec, s[40:41]
	v_mul_f32_e32 v0, v15, v0
	s_nop 1
	v_mov_b32_dpp v1, v0 quad_perm:[1,0,3,2] row_mask:0xf bank_mask:0xf
	s_and_saveexec_b64 s[40:41], s[38:39]
	s_cbranch_execz .LBB0_657
	s_waitcnt lgkmcnt(0)
	v_cvt_pk_bf16_f32 v2, v0, v1
	v_add_co_u32_e32 v0, vcc, 0x1b000, v80
	s_nop 1
	v_addc_co_u32_e32 v1, vcc, 0, v81, vcc
	global_store_dword v[0:1], v2, off offset:3648
